# MLA key up-projection epilogue (per-row rstd scale, bf16 rows) also transposed through LDS for full-line stores; pre-epilogue barrier unconditional in both kv-tile code paths
# speedup vs baseline: 1.0050x; 1.0050x over previous
;   DI bf16_t* kn() const { return (bf16_t*)(ws + OFF_KN); }
; DI void store_bf4(bf16_t* dst, float a, float b, float c, float d) { u32x2 w; w.x = pk_bf16(a, b); w.y = pk_bf16(c, d); *(u32x2*)dst = w; }
;   DI void operator()(const f32x16 (&acc)[2][4], int mbase, int nbase, int l32, int g) const {
; #pragma unroll
;     for (int nb = 0; nb < 2; ++nb)
; #pragma unroll
;       for (int mb = 0; mb < 4; ++mb) {
;         const size_t tok = mbase + 32 * mb + l32;
;         const float r = rs[tok - m0];
; #pragma unroll
;         for (int j = 0; j < 4; ++j) {
;           const int n = nbase - n0 + 32 * nb + 8 * j + 4 * g;
;           store_bf4(p->kn() + tok * 1024 + head * 128 + n, acc[nb][mb][4 * j] * r, acc[nb][mb][4 * j + 1] * r, acc[nb][mb][4 * j + 2] * r, acc[nb][mb][4 * j + 3] * r);
;         }
;       }
;   }
.LBB0_1007:
	ds_read_b128 v[194:197], v227 offset:36960
	ds_read_b128 v[198:201], v227 offset:41568
	ds_read_b128 v[202:205], v226 offset:96
	ds_read_b128 v[220:223], v226 offset:4704
	s_setprio 1
	s_waitcnt lgkmcnt(1)
	v_mfma_f32_32x32x16_bf16 v[112:127], v[194:197], v[202:205], v[112:127]
	v_mfma_f32_32x32x16_bf16 v[48:63], v[198:201], v[202:205], v[48:63]
	s_waitcnt lgkmcnt(0)
	v_mfma_f32_32x32x16_bf16 v[96:111], v[194:197], v[220:223], v[96:111]
	v_mfma_f32_32x32x16_bf16 v[32:47], v[198:201], v[220:223], v[32:47]
	ds_read_b128 v[202:205], v226 offset:9312
	ds_read_b128 v[220:223], v226 offset:13920
	s_waitcnt lgkmcnt(1)
	v_mfma_f32_32x32x16_bf16 v[80:95], v[194:197], v[202:205], v[80:95]
	v_mfma_f32_32x32x16_bf16 v[16:31], v[198:201], v[202:205], v[16:31]
	s_waitcnt lgkmcnt(0)
	v_mfma_f32_32x32x16_bf16 v[64:79], v[194:197], v[220:223], v[64:79]
	v_mfma_f32_32x32x16_bf16 v[0:15], v[198:201], v[220:223], v[0:15]
	s_setprio 0
	s_and_b64 vcc, exec, s[52:53]
	s_barrier
.LBB0_1009:
	s_add_i32 s18, 16, 0x24000
	s_lshl_b32 s6, s89, 8
	s_mov_b32 s7, s43
	s_add_u32 s100, s14, s6
	s_addc_u32 s101, s15, s7
	s_lshl_b32 s99, s64, 7
	s_add_u32 s100, s100, s99
	s_addc_u32 s101, s101, 0
	s_lshl_b32 s99, s81, 11
	s_add_u32 s100, s100, s99
	s_addc_u32 s101, s101, 0
	v_or_b32_e32 v196, s81, v219
	v_subrev_u32_e32 v196, s78, v196
	v_lshl_add_u32 v196, v196, 2, s18
	ds_read_b32 v200, v196
	ds_read_b32 v202, v196 offset:128
	ds_read_b32 v204, v196 offset:256
	ds_read_b32 v220, v196 offset:384
	v_and_b32_e32 v194, 63, v206
	v_lshrrev_b32_e32 v195, 3, v194
	v_and_b32_e32 v197, 7, v194
	v_lshlrev_b32_e32 v197, 4, v197
	v_lshl_add_u32 v198, v195, 11, v197
	v_lshrrev_b32_e32 v199, 6, v206
	v_mov_b32_e32 v194, 0x1200
	v_mul_u32_u24_e32 v199, v199, v194
	v_add_u32_e32 v199, 0x12000, v199
	v_mov_b32_e32 v194, 0x90
	v_mad_u32_u24 v195, v195, v194, v199
	v_add_u32_e32 v195, v195, v197
	v_mad_u32_u24 v197, v219, v194, v199
	v_lshl_add_u32 v197, v218, 4, v197
	s_waitcnt lgkmcnt(0)
	v_pk_mul_f32 v[112:113], v[112:113], v[200:201] op_sel_hi:[1,0]
	v_pk_mul_f32 v[114:115], v[114:115], v[200:201] op_sel_hi:[1,0]
	v_pk_mul_f32 v[116:117], v[116:117], v[200:201] op_sel_hi:[1,0]
	v_pk_mul_f32 v[118:119], v[118:119], v[200:201] op_sel_hi:[1,0]
	v_pk_mul_f32 v[120:121], v[120:121], v[200:201] op_sel_hi:[1,0]
	v_pk_mul_f32 v[122:123], v[122:123], v[200:201] op_sel_hi:[1,0]
	v_pk_mul_f32 v[124:125], v[124:125], v[200:201] op_sel_hi:[1,0]
	v_pk_mul_f32 v[126:127], v[126:127], v[200:201] op_sel_hi:[1,0]
	v_pk_mul_f32 v[48:49], v[48:49], v[200:201] op_sel_hi:[1,0]
	v_pk_mul_f32 v[50:51], v[50:51], v[200:201] op_sel_hi:[1,0]
	v_pk_mul_f32 v[52:53], v[52:53], v[200:201] op_sel_hi:[1,0]
	v_pk_mul_f32 v[54:55], v[54:55], v[200:201] op_sel_hi:[1,0]
	v_pk_mul_f32 v[56:57], v[56:57], v[200:201] op_sel_hi:[1,0]
	v_pk_mul_f32 v[58:59], v[58:59], v[200:201] op_sel_hi:[1,0]
	v_pk_mul_f32 v[60:61], v[60:61], v[200:201] op_sel_hi:[1,0]
	v_pk_mul_f32 v[62:63], v[62:63], v[200:201] op_sel_hi:[1,0]
	v_cvt_pk_bf16_f32 v112, v112, v113
	v_cvt_pk_bf16_f32 v113, v114, v115
	v_cvt_pk_bf16_f32 v114, v116, v117
	v_cvt_pk_bf16_f32 v115, v118, v119
	v_cvt_pk_bf16_f32 v120, v120, v121
	v_cvt_pk_bf16_f32 v121, v122, v123
	v_cvt_pk_bf16_f32 v122, v124, v125
	v_cvt_pk_bf16_f32 v123, v126, v127
	v_cvt_pk_bf16_f32 v48, v48, v49
	v_cvt_pk_bf16_f32 v49, v50, v51
	v_cvt_pk_bf16_f32 v50, v52, v53
	v_cvt_pk_bf16_f32 v51, v54, v55
	v_cvt_pk_bf16_f32 v56, v56, v57
	v_cvt_pk_bf16_f32 v57, v58, v59
	v_cvt_pk_bf16_f32 v58, v60, v61
	v_cvt_pk_bf16_f32 v59, v62, v63
	s_nop 1
	v_permlane32_swap_b32_e32 v112, v114
	v_permlane32_swap_b32_e32 v113, v115
	v_permlane32_swap_b32_e32 v120, v122
	v_permlane32_swap_b32_e32 v121, v123
	v_permlane32_swap_b32_e32 v48, v50
	v_permlane32_swap_b32_e32 v49, v51
	v_permlane32_swap_b32_e32 v56, v58
	v_permlane32_swap_b32_e32 v57, v59
	ds_write_b128 v197, v[112:115]
	ds_write_b128 v197, v[120:123] offset:32
	ds_write_b128 v197, v[48:51] offset:64
	ds_write_b128 v197, v[56:59] offset:96
	ds_read_b128 v[116:119], v195
	ds_read_b128 v[124:127], v195 offset:1152
	ds_read_b128 v[52:55], v195 offset:2304
	ds_read_b128 v[60:63], v195 offset:3456
	v_pk_mul_f32 v[96:97], v[96:97], v[202:203] op_sel_hi:[1,0]
	v_pk_mul_f32 v[98:99], v[98:99], v[202:203] op_sel_hi:[1,0]
	v_pk_mul_f32 v[100:101], v[100:101], v[202:203] op_sel_hi:[1,0]
	v_pk_mul_f32 v[102:103], v[102:103], v[202:203] op_sel_hi:[1,0]
	v_pk_mul_f32 v[104:105], v[104:105], v[202:203] op_sel_hi:[1,0]
	v_pk_mul_f32 v[106:107], v[106:107], v[202:203] op_sel_hi:[1,0]
	v_pk_mul_f32 v[108:109], v[108:109], v[202:203] op_sel_hi:[1,0]
	v_pk_mul_f32 v[110:111], v[110:111], v[202:203] op_sel_hi:[1,0]
	v_pk_mul_f32 v[32:33], v[32:33], v[202:203] op_sel_hi:[1,0]
	v_pk_mul_f32 v[34:35], v[34:35], v[202:203] op_sel_hi:[1,0]
	v_pk_mul_f32 v[36:37], v[36:37], v[202:203] op_sel_hi:[1,0]
	v_pk_mul_f32 v[38:39], v[38:39], v[202:203] op_sel_hi:[1,0]
	v_pk_mul_f32 v[40:41], v[40:41], v[202:203] op_sel_hi:[1,0]
	v_pk_mul_f32 v[42:43], v[42:43], v[202:203] op_sel_hi:[1,0]
	v_pk_mul_f32 v[44:45], v[44:45], v[202:203] op_sel_hi:[1,0]
	v_pk_mul_f32 v[46:47], v[46:47], v[202:203] op_sel_hi:[1,0]
	v_cvt_pk_bf16_f32 v96, v96, v97
	v_cvt_pk_bf16_f32 v97, v98, v99
	v_cvt_pk_bf16_f32 v98, v100, v101
	v_cvt_pk_bf16_f32 v99, v102, v103
	v_cvt_pk_bf16_f32 v104, v104, v105
	v_cvt_pk_bf16_f32 v105, v106, v107
	v_cvt_pk_bf16_f32 v106, v108, v109
	v_cvt_pk_bf16_f32 v107, v110, v111
	v_cvt_pk_bf16_f32 v32, v32, v33
	v_cvt_pk_bf16_f32 v33, v34, v35
	v_cvt_pk_bf16_f32 v34, v36, v37
	v_cvt_pk_bf16_f32 v35, v38, v39
	v_cvt_pk_bf16_f32 v40, v40, v41
	v_cvt_pk_bf16_f32 v41, v42, v43
	v_cvt_pk_bf16_f32 v42, v44, v45
	v_cvt_pk_bf16_f32 v43, v46, v47
	s_nop 1
	v_permlane32_swap_b32_e32 v96, v98
	v_permlane32_swap_b32_e32 v97, v99
	v_permlane32_swap_b32_e32 v104, v106
	v_permlane32_swap_b32_e32 v105, v107
	v_permlane32_swap_b32_e32 v32, v34
	v_permlane32_swap_b32_e32 v33, v35
	v_permlane32_swap_b32_e32 v40, v42
	v_permlane32_swap_b32_e32 v41, v43
	s_waitcnt lgkmcnt(3)
;   DI bf16_t* kn() const { return (bf16_t*)(ws + OFF_KN); }
; DI void store_bf4(bf16_t* dst, float a, float b, float c, float d) { u32x2 w; w.x = pk_bf16(a, b); w.y = pk_bf16(c, d); *(u32x2*)dst = w; }
; DI void store_bf8_pair(bf16_t* rowp  , int g, u32x2 a  , u32x2 b  ) {
;   auto rx = __builtin_amdgcn_permlane32_swap(a.x, b.x, false, false);
;   auto ry = __builtin_amdgcn_permlane32_swap(a.y, b.y, false, false);
;   u32x4 v = {rx[0], ry[0], rx[1], ry[1]};
;   *(u32x4*)(rowp + 8 * g) = v;
; }
;   DI void operator()(const f32x16 (&acc)[2][4], int mbase, int nbase, int l32, int g) const {
; #pragma unroll
;     for (int nb = 0; nb < 2; ++nb)
; #pragma unroll
;       for (int mb = 0; mb < 4; ++mb) {
;         const size_t tok = mbase + 32 * mb + l32;
;         const float r = rs[tok - m0];
; #pragma unroll
;         for (int j = 0; j < 4; ++j) {
;           const int n = nbase - n0 + 32 * nb + 8 * j + 4 * g;
;           store_bf4(p->kn() + tok * 1024 + head * 128 + n, acc[nb][mb][4 * j] * r, acc[nb][mb][4 * j + 1] * r, acc[nb][mb][4 * j + 2] * r, acc[nb][mb][4 * j + 3] * r);
;         }
;       }
;   }
	global_store_dwordx4 v198, v[116:119], s[100:101]
	s_add_u32 s100, s100, 0x4000
	s_addc_u32 s101, s101, 0
	s_waitcnt lgkmcnt(2)
	global_store_dwordx4 v198, v[124:127], s[100:101]
	s_add_u32 s100, s100, 0x4000
	s_addc_u32 s101, s101, 0
	s_waitcnt lgkmcnt(1)
	global_store_dwordx4 v198, v[52:55], s[100:101]
	s_add_u32 s100, s100, 0x4000
	s_addc_u32 s101, s101, 0
	s_waitcnt lgkmcnt(0)
	global_store_dwordx4 v198, v[60:63], s[100:101]
	s_add_u32 s100, s100, 0x4000
	s_addc_u32 s101, s101, 0
	ds_write_b128 v197, v[96:99]
	ds_write_b128 v197, v[104:107] offset:32
	ds_write_b128 v197, v[32:35] offset:64
	ds_write_b128 v197, v[40:43] offset:96
	ds_read_b128 v[100:103], v195
	ds_read_b128 v[108:111], v195 offset:1152
	ds_read_b128 v[36:39], v195 offset:2304
	ds_read_b128 v[44:47], v195 offset:3456
	v_pk_mul_f32 v[80:81], v[80:81], v[204:205] op_sel_hi:[1,0]
	v_pk_mul_f32 v[82:83], v[82:83], v[204:205] op_sel_hi:[1,0]
	v_pk_mul_f32 v[84:85], v[84:85], v[204:205] op_sel_hi:[1,0]
	v_pk_mul_f32 v[86:87], v[86:87], v[204:205] op_sel_hi:[1,0]
	v_pk_mul_f32 v[88:89], v[88:89], v[204:205] op_sel_hi:[1,0]
	v_pk_mul_f32 v[90:91], v[90:91], v[204:205] op_sel_hi:[1,0]
	v_pk_mul_f32 v[92:93], v[92:93], v[204:205] op_sel_hi:[1,0]
	v_pk_mul_f32 v[94:95], v[94:95], v[204:205] op_sel_hi:[1,0]
	v_pk_mul_f32 v[16:17], v[16:17], v[204:205] op_sel_hi:[1,0]
	v_pk_mul_f32 v[18:19], v[18:19], v[204:205] op_sel_hi:[1,0]
	v_pk_mul_f32 v[20:21], v[20:21], v[204:205] op_sel_hi:[1,0]
	v_pk_mul_f32 v[22:23], v[22:23], v[204:205] op_sel_hi:[1,0]
	v_pk_mul_f32 v[24:25], v[24:25], v[204:205] op_sel_hi:[1,0]
	v_pk_mul_f32 v[26:27], v[26:27], v[204:205] op_sel_hi:[1,0]
	v_pk_mul_f32 v[28:29], v[28:29], v[204:205] op_sel_hi:[1,0]
	v_pk_mul_f32 v[30:31], v[30:31], v[204:205] op_sel_hi:[1,0]
	v_cvt_pk_bf16_f32 v80, v80, v81
	v_cvt_pk_bf16_f32 v81, v82, v83
	v_cvt_pk_bf16_f32 v82, v84, v85
	v_cvt_pk_bf16_f32 v83, v86, v87
	v_cvt_pk_bf16_f32 v88, v88, v89
	v_cvt_pk_bf16_f32 v89, v90, v91
	v_cvt_pk_bf16_f32 v90, v92, v93
	v_cvt_pk_bf16_f32 v91, v94, v95
	v_cvt_pk_bf16_f32 v16, v16, v17
	v_cvt_pk_bf16_f32 v17, v18, v19
	v_cvt_pk_bf16_f32 v18, v20, v21
	v_cvt_pk_bf16_f32 v19, v22, v23
	v_cvt_pk_bf16_f32 v24, v24, v25
	v_cvt_pk_bf16_f32 v25, v26, v27
	v_cvt_pk_bf16_f32 v26, v28, v29
	v_cvt_pk_bf16_f32 v27, v30, v31
	s_nop 1
	v_permlane32_swap_b32_e32 v80, v82
	v_permlane32_swap_b32_e32 v81, v83
	v_permlane32_swap_b32_e32 v88, v90
	v_permlane32_swap_b32_e32 v89, v91
	v_permlane32_swap_b32_e32 v16, v18
	v_permlane32_swap_b32_e32 v17, v19
	v_permlane32_swap_b32_e32 v24, v26
	v_permlane32_swap_b32_e32 v25, v27
	s_waitcnt lgkmcnt(3)
	global_store_dwordx4 v198, v[100:103], s[100:101]
	s_add_u32 s100, s100, 0x4000
	s_addc_u32 s101, s101, 0
	s_waitcnt lgkmcnt(2)
	global_store_dwordx4 v198, v[108:111], s[100:101]
	s_add_u32 s100, s100, 0x4000
	s_addc_u32 s101, s101, 0
	s_waitcnt lgkmcnt(1)
	global_store_dwordx4 v198, v[36:39], s[100:101]
	s_add_u32 s100, s100, 0x4000
	s_addc_u32 s101, s101, 0
	s_waitcnt lgkmcnt(0)
	global_store_dwordx4 v198, v[44:47], s[100:101]
	s_add_u32 s100, s100, 0x4000
	s_addc_u32 s101, s101, 0
	ds_write_b128 v197, v[80:83]
	ds_write_b128 v197, v[88:91] offset:32
	ds_write_b128 v197, v[16:19] offset:64
	ds_write_b128 v197, v[24:27] offset:96
	ds_read_b128 v[84:87], v195
	ds_read_b128 v[92:95], v195 offset:1152
	ds_read_b128 v[20:23], v195 offset:2304
	ds_read_b128 v[28:31], v195 offset:3456
	v_pk_mul_f32 v[64:65], v[64:65], v[220:221] op_sel_hi:[1,0]
	v_pk_mul_f32 v[66:67], v[66:67], v[220:221] op_sel_hi:[1,0]
	v_pk_mul_f32 v[68:69], v[68:69], v[220:221] op_sel_hi:[1,0]
	v_pk_mul_f32 v[70:71], v[70:71], v[220:221] op_sel_hi:[1,0]
	v_pk_mul_f32 v[72:73], v[72:73], v[220:221] op_sel_hi:[1,0]
	v_pk_mul_f32 v[74:75], v[74:75], v[220:221] op_sel_hi:[1,0]
	v_pk_mul_f32 v[76:77], v[76:77], v[220:221] op_sel_hi:[1,0]
	v_pk_mul_f32 v[78:79], v[78:79], v[220:221] op_sel_hi:[1,0]
	v_pk_mul_f32 v[0:1], v[0:1], v[220:221] op_sel_hi:[1,0]
	v_pk_mul_f32 v[2:3], v[2:3], v[220:221] op_sel_hi:[1,0]
	v_pk_mul_f32 v[4:5], v[4:5], v[220:221] op_sel_hi:[1,0]
	v_pk_mul_f32 v[6:7], v[6:7], v[220:221] op_sel_hi:[1,0]
	v_pk_mul_f32 v[8:9], v[8:9], v[220:221] op_sel_hi:[1,0]
	v_pk_mul_f32 v[10:11], v[10:11], v[220:221] op_sel_hi:[1,0]
	v_pk_mul_f32 v[12:13], v[12:13], v[220:221] op_sel_hi:[1,0]
	v_pk_mul_f32 v[14:15], v[14:15], v[220:221] op_sel_hi:[1,0]
	v_cvt_pk_bf16_f32 v64, v64, v65
	v_cvt_pk_bf16_f32 v65, v66, v67
	v_cvt_pk_bf16_f32 v66, v68, v69
	v_cvt_pk_bf16_f32 v67, v70, v71
	v_cvt_pk_bf16_f32 v72, v72, v73
	v_cvt_pk_bf16_f32 v73, v74, v75
	v_cvt_pk_bf16_f32 v74, v76, v77
	v_cvt_pk_bf16_f32 v75, v78, v79
	v_cvt_pk_bf16_f32 v0, v0, v1
	v_cvt_pk_bf16_f32 v1, v2, v3
	v_cvt_pk_bf16_f32 v2, v4, v5
	v_cvt_pk_bf16_f32 v3, v6, v7
	v_cvt_pk_bf16_f32 v8, v8, v9
	v_cvt_pk_bf16_f32 v9, v10, v11
	v_cvt_pk_bf16_f32 v10, v12, v13
	v_cvt_pk_bf16_f32 v11, v14, v15
	s_nop 1
	v_permlane32_swap_b32_e32 v64, v66
	v_permlane32_swap_b32_e32 v65, v67
	v_permlane32_swap_b32_e32 v72, v74
	v_permlane32_swap_b32_e32 v73, v75
	v_permlane32_swap_b32_e32 v0, v2
	v_permlane32_swap_b32_e32 v1, v3
	v_permlane32_swap_b32_e32 v8, v10
	v_permlane32_swap_b32_e32 v9, v11
	s_waitcnt lgkmcnt(3)
	global_store_dwordx4 v198, v[84:87], s[100:101]
	s_add_u32 s100, s100, 0x4000
	s_addc_u32 s101, s101, 0
	s_waitcnt lgkmcnt(2)
	global_store_dwordx4 v198, v[92:95], s[100:101]
	s_add_u32 s100, s100, 0x4000
	s_addc_u32 s101, s101, 0
	s_waitcnt lgkmcnt(1)
	global_store_dwordx4 v198, v[20:23], s[100:101]
	s_add_u32 s100, s100, 0x4000
	s_addc_u32 s101, s101, 0
	s_waitcnt lgkmcnt(0)
	global_store_dwordx4 v198, v[28:31], s[100:101]
	s_add_u32 s100, s100, 0x4000
	s_addc_u32 s101, s101, 0
	ds_write_b128 v197, v[64:67]
	ds_write_b128 v197, v[72:75] offset:32
	ds_write_b128 v197, v[0:3] offset:64
	ds_write_b128 v197, v[8:11] offset:96
	ds_read_b128 v[68:71], v195
	ds_read_b128 v[76:79], v195 offset:1152
	ds_read_b128 v[4:7], v195 offset:2304
	ds_read_b128 v[12:15], v195 offset:3456
	s_waitcnt lgkmcnt(3)
	global_store_dwordx4 v198, v[68:71], s[100:101]
	s_add_u32 s100, s100, 0x4000
	s_addc_u32 s101, s101, 0
	s_waitcnt lgkmcnt(2)
	global_store_dwordx4 v198, v[76:79], s[100:101]
	s_add_u32 s100, s100, 0x4000
	s_addc_u32 s101, s101, 0
	s_waitcnt lgkmcnt(1)
	global_store_dwordx4 v198, v[4:7], s[100:101]
	s_add_u32 s100, s100, 0x4000
	s_addc_u32 s101, s101, 0
	s_waitcnt lgkmcnt(0)
	global_store_dwordx4 v198, v[12:15], s[100:101]
	s_add_u32 s100, s100, 0x4000
	s_addc_u32 s101, s101, 0
	s_waitcnt vmcnt(16)
	s_mov_b64 s[6:7], 0

; template <bool trans>
; DI void gemm_core(const GTile& tl, const GTile& nx, bool has_next  , bool chain  , bool pre, u32x4 (&ra)[4], u32x4 (&rb)[4], char* smem, f32x16 (&acc)[2][4]) {
;     ...
;   const int nk = K / 64;
;   if (!pre) { G_LOAD(0); G_STORE(0); G_LOAD(1); }
;   for (int kt = 0; kt < nk; ++kt) {
;     __syncthreads();
;     G_COMPUTE(kt & 1, kt);
;   }
.LBB0_1016:
	s_and_b32 s16, s7, 1
	s_xor_b32 s17, s16, 1
	s_mul_i32 s17, s17, 0x12000
	v_add_u32_e32 v221, s17, v220
	s_waitcnt lgkmcnt(0)
	s_barrier
	v_lshl_add_u64 v[238:239], v[196:197], 0, s[2:3]
	s_waitcnt vmcnt(7)
	ds_write_b128 v221, v[128:131]
	s_waitcnt vmcnt(3)
	ds_write_b128 v221, v[140:143] offset:36864
	v_lshl_add_u64 v[222:223], v[198:199], 0, s[2:3]
	global_load_dwordx4 v[128:131], v[238:239], off offset:256
	global_load_dwordx4 v[140:143], v[222:223], off
	s_mul_i32 s16, s16, 0x12000
	s_add_i32 s16, s16, 16
	v_add3_u32 v241, s16, v205, v192
	v_add3_u32 v240, s16, v204, v192
	ds_read_b128 v[222:225], v241 offset:36864
	ds_read_b128 v[226:229], v241 offset:41472
	ds_read_b128 v[230:233], v240
	ds_read_b128 v[234:237], v240 offset:4608
	s_add_i32 s7, s7, 1
	s_setprio 1
	s_waitcnt lgkmcnt(1)
	v_mfma_f32_32x32x16_bf16 v[112:127], v[230:233], v[222:225], v[112:127]
	v_mfma_f32_32x32x16_bf16 v[48:63], v[230:233], v[226:229], v[48:63]
	s_waitcnt lgkmcnt(0)
	v_mfma_f32_32x32x16_bf16 v[96:111], v[234:237], v[222:225], v[96:111]
	v_mfma_f32_32x32x16_bf16 v[32:47], v[234:237], v[226:229], v[32:47]
	ds_read_b128 v[230:233], v240 offset:9216
	ds_read_b128 v[234:237], v240 offset:13824
	s_waitcnt lgkmcnt(1)
	v_mfma_f32_32x32x16_bf16 v[80:95], v[230:233], v[222:225], v[80:95]
	v_mfma_f32_32x32x16_bf16 v[16:31], v[230:233], v[226:229], v[16:31]
	s_waitcnt lgkmcnt(0)
	v_mfma_f32_32x32x16_bf16 v[64:79], v[234:237], v[222:225], v[64:79]
	v_mfma_f32_32x32x16_bf16 v[0:15], v[234:237], v[226:229], v[0:15]
	s_setprio 0
	ds_write_b128 v221, v[132:135] offset:9216
	s_waitcnt vmcnt(4)
	ds_write_b128 v221, v[148:151] offset:46080
	v_add_co_u32_e32 v132, vcc, s41, v238
	v_lshl_add_u64 v[148:149], v[200:201], 0, s[2:3]
	s_nop 0
	v_addc_co_u32_e32 v133, vcc, 0, v239, vcc
	global_load_dwordx4 v[132:135], v[132:133], off offset:256
	s_nop 0
	global_load_dwordx4 v[148:151], v[148:149], off
	ds_read_b128 v[222:225], v241 offset:36896
	ds_read_b128 v[226:229], v241 offset:41504
	ds_read_b128 v[230:233], v240 offset:32
	ds_read_b128 v[234:237], v240 offset:4640
	s_setprio 1
	s_waitcnt lgkmcnt(1)
	v_mfma_f32_32x32x16_bf16 v[112:127], v[230:233], v[222:225], v[112:127]
	v_mfma_f32_32x32x16_bf16 v[48:63], v[230:233], v[226:229], v[48:63]
	s_waitcnt lgkmcnt(0)
	v_mfma_f32_32x32x16_bf16 v[96:111], v[234:237], v[222:225], v[96:111]
	v_mfma_f32_32x32x16_bf16 v[32:47], v[234:237], v[226:229], v[32:47]
	ds_read_b128 v[230:233], v240 offset:9248
	ds_read_b128 v[234:237], v240 offset:13856
	s_waitcnt lgkmcnt(1)
	v_mfma_f32_32x32x16_bf16 v[80:95], v[230:233], v[222:225], v[80:95]
	v_mfma_f32_32x32x16_bf16 v[16:31], v[230:233], v[226:229], v[16:31]
	s_waitcnt lgkmcnt(0)
	v_mfma_f32_32x32x16_bf16 v[64:79], v[234:237], v[222:225], v[64:79]
	v_mfma_f32_32x32x16_bf16 v[0:15], v[234:237], v[226:229], v[0:15]
	s_setprio 0
	ds_write_b128 v221, v[136:139] offset:18432
	s_waitcnt vmcnt(5)
	ds_write_b128 v221, v[152:155] offset:55296
	v_add_co_u32_e32 v136, vcc, s56, v238
	v_lshl_add_u64 v[152:153], v[202:203], 0, s[2:3]
	s_nop 0
	v_addc_co_u32_e32 v137, vcc, 0, v239, vcc
	global_load_dwordx4 v[136:139], v[136:137], off offset:256
	s_nop 0
	global_load_dwordx4 v[152:155], v[152:153], off
	ds_read_b128 v[222:225], v241 offset:36928
	ds_read_b128 v[226:229], v241 offset:41536
	ds_read_b128 v[230:233], v240 offset:64
	ds_read_b128 v[234:237], v240 offset:4672
	s_setprio 1
	s_waitcnt lgkmcnt(1)
	v_mfma_f32_32x32x16_bf16 v[112:127], v[230:233], v[222:225], v[112:127]
	v_mfma_f32_32x32x16_bf16 v[48:63], v[230:233], v[226:229], v[48:63]
	s_waitcnt lgkmcnt(0)
	v_mfma_f32_32x32x16_bf16 v[96:111], v[234:237], v[222:225], v[96:111]
	v_mfma_f32_32x32x16_bf16 v[32:47], v[234:237], v[226:229], v[32:47]
	ds_read_b128 v[230:233], v240 offset:9280
	ds_read_b128 v[234:237], v240 offset:13888
	s_waitcnt lgkmcnt(1)
	v_mfma_f32_32x32x16_bf16 v[80:95], v[230:233], v[222:225], v[80:95]
	v_mfma_f32_32x32x16_bf16 v[16:31], v[230:233], v[226:229], v[16:31]
	s_waitcnt lgkmcnt(0)
	v_mfma_f32_32x32x16_bf16 v[64:79], v[234:237], v[222:225], v[64:79]
	v_mfma_f32_32x32x16_bf16 v[0:15], v[234:237], v[226:229], v[0:15]
	s_setprio 0
	ds_write_b128 v221, v[144:147] offset:27648
	s_waitcnt vmcnt(6)
	ds_write_b128 v221, v[156:159] offset:64512
	v_add_co_u32_e32 v144, vcc, s57, v238
	v_lshl_add_u64 v[156:157], v[194:195], 0, s[2:3]
	s_nop 0
	v_addc_co_u32_e32 v145, vcc, 0, v239, vcc
	global_load_dwordx4 v[144:147], v[144:145], off offset:256
	s_nop 0
	global_load_dwordx4 v[156:159], v[156:157], off
	ds_read_b128 v[222:225], v241 offset:36960
	ds_read_b128 v[226:229], v241 offset:41568
	ds_read_b128 v[230:233], v240 offset:96
	ds_read_b128 v[234:237], v240 offset:4704
	s_setprio 1
	s_waitcnt lgkmcnt(1)
	v_mfma_f32_32x32x16_bf16 v[112:127], v[230:233], v[222:225], v[112:127]
	v_mfma_f32_32x32x16_bf16 v[48:63], v[230:233], v[226:229], v[48:63]
	s_waitcnt lgkmcnt(0)
	v_mfma_f32_32x32x16_bf16 v[96:111], v[234:237], v[222:225], v[96:111]
	v_mfma_f32_32x32x16_bf16 v[32:47], v[234:237], v[226:229], v[32:47]
	ds_read_b128 v[230:233], v240 offset:9312
	ds_read_b128 v[234:237], v240 offset:13920
	s_waitcnt lgkmcnt(1)
	v_mfma_f32_32x32x16_bf16 v[80:95], v[230:233], v[222:225], v[80:95]
	v_mfma_f32_32x32x16_bf16 v[16:31], v[230:233], v[226:229], v[16:31]
	s_waitcnt lgkmcnt(0)
	v_mfma_f32_32x32x16_bf16 v[64:79], v[234:237], v[222:225], v[64:79]
	v_mfma_f32_32x32x16_bf16 v[0:15], v[234:237], v[226:229], v[0:15]
	s_setprio 0
	s_add_u32 s2, s2, 0x80
	s_addc_u32 s3, s3, 0
	s_cmp_eq_u32 s6, s7
	s_cbranch_scc0 .LBB0_1016
	s_and_b32 s2, s6, 1
	s_mul_i32 s3, s2, 0x12000
	s_xor_b32 s2, s2, 1
	s_mul_i32 s2, s2, 0x12000
	s_add_i32 s3, s3, 16
	v_add_u32_e32 v228, s2, v220
	s_barrier
; template <bool trans>
; DI void gemm_core(const GTile& tl, const GTile& nx, bool has_next  , bool chain  , bool pre, u32x4 (&ra)[4], u32x4 (&rb)[4], char* smem, f32x16 (&acc)[2][4]) {
;     ...
;   const int nk = K / 64;
;   if (!pre) { G_LOAD(0); G_STORE(0); G_LOAD(1); }
;   for (int kt = 0; kt < nk; ++kt) {
;     __syncthreads();
;     G_COMPUTE(kt & 1, kt);
;   }
	v_add3_u32 v203, s3, v205, v192
	s_waitcnt vmcnt(7)
	ds_write_b128 v228, v[128:131]
	s_waitcnt vmcnt(6)
	ds_write_b128 v228, v[140:143] offset:36864
	v_add3_u32 v202, s3, v204, v192
	ds_read_b128 v[194:197], v203 offset:36864
	ds_read_b128 v[198:201], v203 offset:41472
	ds_read_b128 v[220:223], v202
	ds_read_b128 v[224:227], v202 offset:4608
	s_setprio 1
	s_waitcnt lgkmcnt(1)
	v_mfma_f32_32x32x16_bf16 v[112:127], v[220:223], v[194:197], v[112:127]
	v_mfma_f32_32x32x16_bf16 v[48:63], v[220:223], v[198:201], v[48:63]
	s_waitcnt lgkmcnt(0)
	v_mfma_f32_32x32x16_bf16 v[96:111], v[224:227], v[194:197], v[96:111]
	v_mfma_f32_32x32x16_bf16 v[32:47], v[224:227], v[198:201], v[32:47]
	ds_read_b128 v[220:223], v202 offset:9216
	ds_read_b128 v[224:227], v202 offset:13824
	s_waitcnt lgkmcnt(1)
	v_mfma_f32_32x32x16_bf16 v[80:95], v[220:223], v[194:197], v[80:95]
	v_mfma_f32_32x32x16_bf16 v[16:31], v[220:223], v[198:201], v[16:31]
	s_waitcnt lgkmcnt(0)
	v_mfma_f32_32x32x16_bf16 v[64:79], v[224:227], v[194:197], v[64:79]
	v_mfma_f32_32x32x16_bf16 v[0:15], v[224:227], v[198:201], v[0:15]
	s_setprio 0
	s_waitcnt vmcnt(5)
	ds_write_b128 v228, v[132:135] offset:9216
	s_waitcnt vmcnt(4)
	ds_write_b128 v228, v[148:151] offset:46080
	ds_read_b128 v[194:197], v203 offset:36896
	ds_read_b128 v[198:201], v203 offset:41504
	ds_read_b128 v[220:223], v202 offset:32
	ds_read_b128 v[224:227], v202 offset:4640
	s_setprio 1
	s_waitcnt lgkmcnt(1)
	v_mfma_f32_32x32x16_bf16 v[112:127], v[220:223], v[194:197], v[112:127]
	v_mfma_f32_32x32x16_bf16 v[48:63], v[220:223], v[198:201], v[48:63]
	s_waitcnt lgkmcnt(0)
	v_mfma_f32_32x32x16_bf16 v[96:111], v[224:227], v[194:197], v[96:111]
	v_mfma_f32_32x32x16_bf16 v[32:47], v[224:227], v[198:201], v[32:47]
	ds_read_b128 v[220:223], v202 offset:9248
	ds_read_b128 v[224:227], v202 offset:13856
	s_waitcnt lgkmcnt(1)
	v_mfma_f32_32x32x16_bf16 v[80:95], v[220:223], v[194:197], v[80:95]
	v_mfma_f32_32x32x16_bf16 v[16:31], v[220:223], v[198:201], v[16:31]
	s_waitcnt lgkmcnt(0)
	v_mfma_f32_32x32x16_bf16 v[64:79], v[224:227], v[194:197], v[64:79]
	v_mfma_f32_32x32x16_bf16 v[0:15], v[224:227], v[198:201], v[0:15]
	s_setprio 0
	s_waitcnt vmcnt(3)
	ds_write_b128 v228, v[136:139] offset:18432
	s_waitcnt vmcnt(2)
	ds_write_b128 v228, v[152:155] offset:55296
	ds_read_b128 v[194:197], v203 offset:36928
	ds_read_b128 v[198:201], v203 offset:41536
	ds_read_b128 v[220:223], v202 offset:64
	ds_read_b128 v[224:227], v202 offset:4672
	s_setprio 1
	s_waitcnt lgkmcnt(1)
	v_mfma_f32_32x32x16_bf16 v[112:127], v[220:223], v[194:197], v[112:127]
	v_mfma_f32_32x32x16_bf16 v[48:63], v[220:223], v[198:201], v[48:63]
	s_waitcnt lgkmcnt(0)
	v_mfma_f32_32x32x16_bf16 v[96:111], v[224:227], v[194:197], v[96:111]
	v_mfma_f32_32x32x16_bf16 v[32:47], v[224:227], v[198:201], v[32:47]
	ds_read_b128 v[220:223], v202 offset:9280
	ds_read_b128 v[224:227], v202 offset:13888
	s_waitcnt lgkmcnt(1)
	v_mfma_f32_32x32x16_bf16 v[80:95], v[220:223], v[194:197], v[80:95]
	v_mfma_f32_32x32x16_bf16 v[16:31], v[220:223], v[198:201], v[16:31]
	s_waitcnt lgkmcnt(0)
	v_mfma_f32_32x32x16_bf16 v[64:79], v[224:227], v[194:197], v[64:79]
	v_mfma_f32_32x32x16_bf16 v[0:15], v[224:227], v[198:201], v[0:15]
	s_setprio 0
	s_waitcnt vmcnt(1)
	ds_write_b128 v228, v[144:147] offset:27648
	s_waitcnt vmcnt(0)
	ds_write_b128 v228, v[156:159] offset:64512
	ds_read_b128 v[194:197], v203 offset:36960
	ds_read_b128 v[198:201], v203 offset:41568
	ds_read_b128 v[220:223], v202 offset:96
	ds_read_b128 v[224:227], v202 offset:4704
	s_setprio 1
	s_waitcnt lgkmcnt(1)
	v_mfma_f32_32x32x16_bf16 v[112:127], v[220:223], v[194:197], v[112:127]
	v_mfma_f32_32x32x16_bf16 v[48:63], v[220:223], v[198:201], v[48:63]
	s_waitcnt lgkmcnt(0)
	v_mfma_f32_32x32x16_bf16 v[96:111], v[224:227], v[194:197], v[96:111]
	v_mfma_f32_32x32x16_bf16 v[32:47], v[224:227], v[198:201], v[32:47]
	ds_read_b128 v[220:223], v202 offset:9312
	ds_read_b128 v[224:227], v202 offset:13920
	s_waitcnt lgkmcnt(1)
	v_mfma_f32_32x32x16_bf16 v[80:95], v[220:223], v[194:197], v[80:95]
	v_mfma_f32_32x32x16_bf16 v[16:31], v[220:223], v[198:201], v[16:31]
	s_waitcnt lgkmcnt(0)
	v_mfma_f32_32x32x16_bf16 v[64:79], v[224:227], v[194:197], v[64:79]
	v_mfma_f32_32x32x16_bf16 v[0:15], v[224:227], v[198:201], v[0:15]
	s_setprio 0
	s_add_i32 s2, 16, 0x12000
	v_add3_u32 v224, s2, v204, v192
	v_add3_u32 v192, s59, v205, v192
	s_barrier
; template <bool trans>
; DI void gemm_core(const GTile& tl, const GTile& nx, bool has_next  , bool chain  , bool pre, u32x4 (&ra)[4], u32x4 (&rb)[4], char* smem, f32x16 (&acc)[2][4]) {
;     ...
;   const int nk = K / 64;
;   if (!pre) { G_LOAD(0); G_STORE(0); G_LOAD(1); }
;   for (int kt = 0; kt < nk; ++kt) {
;     __syncthreads();
;     G_COMPUTE(kt & 1, kt);
;   }
;   if (!has_next) __syncthreads();
	ds_read_b128 v[194:197], v192
	ds_read_b128 v[198:201], v192 offset:4608
	ds_read_b128 v[202:205], v224
	ds_read_b128 v[220:223], v224 offset:4608
	s_setprio 1
	s_waitcnt lgkmcnt(1)
	v_mfma_f32_32x32x16_bf16 v[112:127], v[202:205], v[194:197], v[112:127]
	v_mfma_f32_32x32x16_bf16 v[48:63], v[202:205], v[198:201], v[48:63]
	s_waitcnt lgkmcnt(0)
	v_mfma_f32_32x32x16_bf16 v[96:111], v[220:223], v[194:197], v[96:111]
	v_mfma_f32_32x32x16_bf16 v[32:47], v[220:223], v[198:201], v[32:47]
	ds_read_b128 v[202:205], v224 offset:9216
	ds_read_b128 v[220:223], v224 offset:13824
	s_waitcnt lgkmcnt(1)
	v_mfma_f32_32x32x16_bf16 v[80:95], v[202:205], v[194:197], v[80:95]
	v_mfma_f32_32x32x16_bf16 v[16:31], v[202:205], v[198:201], v[16:31]
	s_waitcnt lgkmcnt(0)
	v_mfma_f32_32x32x16_bf16 v[64:79], v[220:223], v[194:197], v[64:79]
	v_mfma_f32_32x32x16_bf16 v[0:15], v[220:223], v[198:201], v[0:15]
	s_setprio 0
	ds_read_b128 v[194:197], v192 offset:32
	ds_read_b128 v[198:201], v192 offset:4640
	ds_read_b128 v[202:205], v224 offset:32
	ds_read_b128 v[220:223], v224 offset:4640
	s_setprio 1
	s_waitcnt lgkmcnt(1)
	v_mfma_f32_32x32x16_bf16 v[112:127], v[202:205], v[194:197], v[112:127]
	v_mfma_f32_32x32x16_bf16 v[48:63], v[202:205], v[198:201], v[48:63]
	s_waitcnt lgkmcnt(0)
	v_mfma_f32_32x32x16_bf16 v[96:111], v[220:223], v[194:197], v[96:111]
	v_mfma_f32_32x32x16_bf16 v[32:47], v[220:223], v[198:201], v[32:47]
	ds_read_b128 v[202:205], v224 offset:9248
	ds_read_b128 v[220:223], v224 offset:13856
	s_waitcnt lgkmcnt(1)
	v_mfma_f32_32x32x16_bf16 v[80:95], v[202:205], v[194:197], v[80:95]
	v_mfma_f32_32x32x16_bf16 v[16:31], v[202:205], v[198:201], v[16:31]
	s_waitcnt lgkmcnt(0)
	v_mfma_f32_32x32x16_bf16 v[64:79], v[220:223], v[194:197], v[64:79]
	v_mfma_f32_32x32x16_bf16 v[0:15], v[220:223], v[198:201], v[0:15]
	s_setprio 0
	ds_read_b128 v[194:197], v192 offset:64
	ds_read_b128 v[198:201], v192 offset:4672
	ds_read_b128 v[202:205], v224 offset:64
	ds_read_b128 v[220:223], v224 offset:4672
	s_setprio 1
	s_waitcnt lgkmcnt(1)
	v_mfma_f32_32x32x16_bf16 v[112:127], v[202:205], v[194:197], v[112:127]
	v_mfma_f32_32x32x16_bf16 v[48:63], v[202:205], v[198:201], v[48:63]
	s_waitcnt lgkmcnt(0)
	v_mfma_f32_32x32x16_bf16 v[96:111], v[220:223], v[194:197], v[96:111]
	v_mfma_f32_32x32x16_bf16 v[32:47], v[220:223], v[198:201], v[32:47]
	ds_read_b128 v[202:205], v224 offset:9280
	ds_read_b128 v[220:223], v224 offset:13888
	s_waitcnt lgkmcnt(1)
	v_mfma_f32_32x32x16_bf16 v[80:95], v[202:205], v[194:197], v[80:95]
	v_mfma_f32_32x32x16_bf16 v[16:31], v[202:205], v[198:201], v[16:31]
	s_waitcnt lgkmcnt(0)
	v_mfma_f32_32x32x16_bf16 v[64:79], v[220:223], v[194:197], v[64:79]
	v_mfma_f32_32x32x16_bf16 v[0:15], v[220:223], v[198:201], v[0:15]
	s_setprio 0
	ds_read_b128 v[194:197], v192 offset:96
	ds_read_b128 v[198:201], v192 offset:4704
	ds_read_b128 v[202:205], v224 offset:96
	ds_read_b128 v[220:223], v224 offset:4704
	s_setprio 1
	s_waitcnt lgkmcnt(1)
	v_mfma_f32_32x32x16_bf16 v[112:127], v[202:205], v[194:197], v[112:127]
	v_mfma_f32_32x32x16_bf16 v[48:63], v[202:205], v[198:201], v[48:63]
	s_waitcnt lgkmcnt(0)
	v_mfma_f32_32x32x16_bf16 v[96:111], v[220:223], v[194:197], v[96:111]
	v_mfma_f32_32x32x16_bf16 v[32:47], v[220:223], v[198:201], v[32:47]
	ds_read_b128 v[202:205], v224 offset:9312
	ds_read_b128 v[220:223], v224 offset:13920
	s_waitcnt lgkmcnt(1)
	v_mfma_f32_32x32x16_bf16 v[80:95], v[202:205], v[194:197], v[80:95]
	v_mfma_f32_32x32x16_bf16 v[16:31], v[202:205], v[198:201], v[16:31]
	s_waitcnt lgkmcnt(0)
	v_mfma_f32_32x32x16_bf16 v[64:79], v[220:223], v[194:197], v[64:79]
	v_mfma_f32_32x32x16_bf16 v[0:15], v[220:223], v[198:201], v[0:15]
	s_setprio 0
	s_and_b64 vcc, exec, s[52:53]
	s_barrier
